# last two LDS-DMA pieces of the 6-piece loader segments issued inside the wave's own MFMA block (vmcnt(6)), on top of v45
# baseline (speedup 1.0000x reference)
.LBB0_233:
	ds_read_b128 v[130:133], v213
	ds_read_b128 v[134:137], v214
	ds_read_b128 v[138:141], v215
	ds_read_b128 v[142:145], v216
	ds_read_b128 v[146:149], v217
	ds_read_b128 v[150:153], v218
	ds_read_b128 v[154:157], v219
	ds_read_b128 v[158:161], v220
	s_add_i32 s4, s33, 0xffffe080
	s_cmp_eq_u32 s58, 12
	s_cselect_b32 s61, s18, s4
	s_cselect_b32 s60, s19, s57
	s_add_i32 s59, s61, 0x80
	s_mov_b32 s4, s70
	s_mov_b32 m0, s38
	ds_read_b128 v[162:165], v221
	ds_read_b128 v[166:169], v221 offset:2048
	ds_read_b128 v[170:173], v222
	ds_read_b128 v[174:177], v222 offset:2048
	ds_read_b128 v[178:181], v221 offset:4096
	ds_read_b128 v[182:185], v221 offset:6144
	ds_read_b128 v[186:189], v222 offset:4096
	ds_read_b128 v[190:193], v222 offset:6144
	buffer_load_dwordx4 v207, s[4:7], s33 offen lds
	s_mov_b32 m0, s41
	s_nop 0
	buffer_load_dwordx4 v209, s[4:7], s33 offen lds
	s_waitcnt vmcnt(8)
	s_waitcnt lgkmcnt(0)
	s_barrier
	s_setprio 1
	s_waitcnt lgkmcnt(7)
	v_mfma_f32_16x16x32_bf16 v[114:117], v[130:133], v[162:165], v[114:117]
	v_mfma_f32_16x16x32_bf16 v[110:113], v[138:141], v[162:165], v[110:113]
	s_waitcnt lgkmcnt(6)
	v_mfma_f32_16x16x32_bf16 v[106:109], v[130:133], v[166:169], v[106:109]
	v_mfma_f32_16x16x32_bf16 v[102:105], v[138:141], v[166:169], v[102:105]
	s_waitcnt lgkmcnt(3)
	v_mfma_f32_16x16x32_bf16 v[98:101], v[130:133], v[178:181], v[98:101]
	v_mfma_f32_16x16x32_bf16 v[94:97], v[138:141], v[178:181], v[94:97]
	s_waitcnt lgkmcnt(2)
	v_mfma_f32_16x16x32_bf16 v[90:93], v[130:133], v[182:185], v[90:93]
	v_mfma_f32_16x16x32_bf16 v[86:89], v[138:141], v[182:185], v[86:89]
	v_mfma_f32_16x16x32_bf16 v[114:117], v[134:137], v[170:173], v[114:117]
	v_mfma_f32_16x16x32_bf16 v[110:113], v[142:145], v[170:173], v[110:113]
	v_mfma_f32_16x16x32_bf16 v[106:109], v[134:137], v[174:177], v[106:109]
	v_mfma_f32_16x16x32_bf16 v[102:105], v[142:145], v[174:177], v[102:105]
	s_waitcnt lgkmcnt(1)
	v_mfma_f32_16x16x32_bf16 v[98:101], v[134:137], v[186:189], v[98:101]
	v_mfma_f32_16x16x32_bf16 v[94:97], v[142:145], v[186:189], v[94:97]
	s_waitcnt lgkmcnt(0)
	v_mfma_f32_16x16x32_bf16 v[90:93], v[134:137], v[190:193], v[90:93]
	v_mfma_f32_16x16x32_bf16 v[86:89], v[142:145], v[190:193], v[86:89]
	s_setprio 0
	s_setprio 1
	v_mfma_f32_16x16x32_bf16 v[82:85], v[146:149], v[162:165], v[82:85]
	v_mfma_f32_16x16x32_bf16 v[74:77], v[154:157], v[162:165], v[74:77]
	v_mfma_f32_16x16x32_bf16 v[70:73], v[146:149], v[166:169], v[70:73]
	v_mfma_f32_16x16x32_bf16 v[66:69], v[154:157], v[166:169], v[66:69]
	v_mfma_f32_16x16x32_bf16 v[62:65], v[146:149], v[178:181], v[62:65]
	v_mfma_f32_16x16x32_bf16 v[58:61], v[154:157], v[178:181], v[58:61]
	v_mfma_f32_16x16x32_bf16 v[54:57], v[146:149], v[182:185], v[54:57]
	v_mfma_f32_16x16x32_bf16 v[50:53], v[154:157], v[182:185], v[50:53]
	v_mfma_f32_16x16x32_bf16 v[82:85], v[150:153], v[170:173], v[82:85]
	v_mfma_f32_16x16x32_bf16 v[74:77], v[158:161], v[170:173], v[74:77]
	v_mfma_f32_16x16x32_bf16 v[70:73], v[150:153], v[174:177], v[70:73]
	v_mfma_f32_16x16x32_bf16 v[66:69], v[158:161], v[174:177], v[66:69]
	v_mfma_f32_16x16x32_bf16 v[62:65], v[150:153], v[186:189], v[62:65]
	v_mfma_f32_16x16x32_bf16 v[58:61], v[158:161], v[186:189], v[58:61]
	v_mfma_f32_16x16x32_bf16 v[54:57], v[150:153], v[190:193], v[54:57]
	v_mfma_f32_16x16x32_bf16 v[50:53], v[158:161], v[190:193], v[50:53]
	s_setprio 0
	s_barrier
	s_mov_b32 m0, s21
	ds_read_b128 v[162:165], v221 offset:16384
	ds_read_b128 v[166:169], v221 offset:18432
	ds_read_b128 v[170:173], v222 offset:16384
	ds_read_b128 v[174:177], v222 offset:18432
	ds_read_b128 v[178:181], v221 offset:20480
	ds_read_b128 v[182:185], v221 offset:22528
	ds_read_b128 v[186:189], v222 offset:20480
	ds_read_b128 v[190:193], v222 offset:22528
	buffer_load_dwordx4 v208, s[4:7], s60 offen lds
	s_mov_b32 m0, s22
	s_add_i32 s62, s60, 0x40000
	buffer_load_dwordx4 v210, s[4:7], s60 offen lds
	s_mov_b32 m0, s23
	s_nop 0
	buffer_load_dwordx4 v208, s[4:7], s62 offen lds
	s_mov_b32 m0, s24
	s_nop 0
	buffer_load_dwordx4 v210, s[4:7], s62 offen lds
	s_waitcnt vmcnt(6)
	s_waitcnt lgkmcnt(0)
	s_barrier
	s_setprio 1
	s_waitcnt lgkmcnt(7)
	v_mfma_f32_16x16x32_bf16 v[78:81], v[130:133], v[162:165], v[78:81]
	v_mfma_f32_16x16x32_bf16 v[46:49], v[138:141], v[162:165], v[46:49]
	s_waitcnt lgkmcnt(6)
	s_mov_b32 m0, s20
	s_nop 0
	buffer_load_dwordx4 v207, s[4:7], s61 offen lds
	v_mfma_f32_16x16x32_bf16 v[42:45], v[130:133], v[166:169], v[42:45]
	v_mfma_f32_16x16x32_bf16 v[38:41], v[138:141], v[166:169], v[38:41]
	s_waitcnt lgkmcnt(3)
	v_mfma_f32_16x16x32_bf16 v[34:37], v[130:133], v[178:181], v[34:37]
	v_mfma_f32_16x16x32_bf16 v[30:33], v[138:141], v[178:181], v[30:33]
	s_waitcnt lgkmcnt(2)
	s_mov_b32 m0, s25
	s_nop 0
	buffer_load_dwordx4 v209, s[4:7], s61 offen lds
	v_mfma_f32_16x16x32_bf16 v[26:29], v[130:133], v[182:185], v[26:29]
	v_mfma_f32_16x16x32_bf16 v[22:25], v[138:141], v[182:185], v[22:25]
	v_mfma_f32_16x16x32_bf16 v[78:81], v[134:137], v[170:173], v[78:81]
	v_mfma_f32_16x16x32_bf16 v[46:49], v[142:145], v[170:173], v[46:49]
	v_mfma_f32_16x16x32_bf16 v[42:45], v[134:137], v[174:177], v[42:45]
	v_mfma_f32_16x16x32_bf16 v[38:41], v[142:145], v[174:177], v[38:41]
	s_waitcnt lgkmcnt(1)
	v_mfma_f32_16x16x32_bf16 v[34:37], v[134:137], v[186:189], v[34:37]
	v_mfma_f32_16x16x32_bf16 v[30:33], v[142:145], v[186:189], v[30:33]
	s_waitcnt lgkmcnt(0)
	v_mfma_f32_16x16x32_bf16 v[26:29], v[134:137], v[190:193], v[26:29]
	v_mfma_f32_16x16x32_bf16 v[22:25], v[142:145], v[190:193], v[22:25]
	s_setprio 0
	s_setprio 1
	v_mfma_f32_16x16x32_bf16 v[18:21], v[146:149], v[162:165], v[18:21]
	v_mfma_f32_16x16x32_bf16 v[14:17], v[154:157], v[162:165], v[14:17]
	v_mfma_f32_16x16x32_bf16 v[10:13], v[146:149], v[166:169], v[10:13]
	v_mfma_f32_16x16x32_bf16 v[6:9], v[154:157], v[166:169], v[6:9]
	v_mfma_f32_16x16x32_bf16 v[2:5], v[146:149], v[178:181], v[2:5]
	v_mfma_f32_16x16x32_bf16 v[126:129], v[154:157], v[178:181], v[126:129]
	v_mfma_f32_16x16x32_bf16 v[122:125], v[146:149], v[182:185], v[122:125]
	v_mfma_f32_16x16x32_bf16 v[118:121], v[154:157], v[182:185], v[118:121]
	v_mfma_f32_16x16x32_bf16 v[18:21], v[150:153], v[170:173], v[18:21]
	v_mfma_f32_16x16x32_bf16 v[14:17], v[158:161], v[170:173], v[14:17]
	v_mfma_f32_16x16x32_bf16 v[10:13], v[150:153], v[174:177], v[10:13]
	v_mfma_f32_16x16x32_bf16 v[6:9], v[158:161], v[174:177], v[6:9]
	v_mfma_f32_16x16x32_bf16 v[2:5], v[150:153], v[186:189], v[2:5]
	v_mfma_f32_16x16x32_bf16 v[126:129], v[158:161], v[186:189], v[126:129]
	v_mfma_f32_16x16x32_bf16 v[122:125], v[150:153], v[190:193], v[122:125]
	v_mfma_f32_16x16x32_bf16 v[118:121], v[158:161], v[190:193], v[118:121]
	s_setprio 0
	s_barrier
	ds_read_b128 v[130:133], v194
	ds_read_b128 v[134:137], v224
	ds_read_b128 v[138:141], v225
	ds_read_b128 v[142:145], v228
	ds_read_b128 v[146:149], v229
	ds_read_b128 v[150:153], v230
	ds_read_b128 v[154:157], v231
	ds_read_b128 v[158:161], v233
	s_addk_i32 s61, 0x2000
	s_mov_b32 m0, s26
	ds_read_b128 v[162:165], v221 offset:32768
	ds_read_b128 v[166:169], v221 offset:34816
	ds_read_b128 v[170:173], v222 offset:32768
	ds_read_b128 v[174:177], v222 offset:34816
	ds_read_b128 v[178:181], v221 offset:36864
	ds_read_b128 v[182:185], v221 offset:38912
	ds_read_b128 v[186:189], v222 offset:36864
	ds_read_b128 v[190:193], v222 offset:38912
	buffer_load_dwordx4 v207, s[4:7], s61 offen lds
	s_mov_b32 m0, s27
	s_nop 0
	buffer_load_dwordx4 v209, s[4:7], s61 offen lds
	s_waitcnt vmcnt(8)
	s_waitcnt lgkmcnt(0)
	s_barrier
	s_setprio 1
	s_waitcnt lgkmcnt(7)
	v_mfma_f32_16x16x32_bf16 v[114:117], v[130:133], v[162:165], v[114:117]
	v_mfma_f32_16x16x32_bf16 v[110:113], v[138:141], v[162:165], v[110:113]
	s_waitcnt lgkmcnt(6)
	v_mfma_f32_16x16x32_bf16 v[106:109], v[130:133], v[166:169], v[106:109]
	v_mfma_f32_16x16x32_bf16 v[102:105], v[138:141], v[166:169], v[102:105]
	s_waitcnt lgkmcnt(3)
	v_mfma_f32_16x16x32_bf16 v[98:101], v[130:133], v[178:181], v[98:101]
	v_mfma_f32_16x16x32_bf16 v[94:97], v[138:141], v[178:181], v[94:97]
	s_waitcnt lgkmcnt(2)
	v_mfma_f32_16x16x32_bf16 v[90:93], v[130:133], v[182:185], v[90:93]
	v_mfma_f32_16x16x32_bf16 v[86:89], v[138:141], v[182:185], v[86:89]
	v_mfma_f32_16x16x32_bf16 v[114:117], v[134:137], v[170:173], v[114:117]
	v_mfma_f32_16x16x32_bf16 v[110:113], v[142:145], v[170:173], v[110:113]
	v_mfma_f32_16x16x32_bf16 v[106:109], v[134:137], v[174:177], v[106:109]
	v_mfma_f32_16x16x32_bf16 v[102:105], v[142:145], v[174:177], v[102:105]
	s_waitcnt lgkmcnt(1)
	v_mfma_f32_16x16x32_bf16 v[98:101], v[134:137], v[186:189], v[98:101]
	v_mfma_f32_16x16x32_bf16 v[94:97], v[142:145], v[186:189], v[94:97]
	s_waitcnt lgkmcnt(0)
	v_mfma_f32_16x16x32_bf16 v[90:93], v[134:137], v[190:193], v[90:93]
	v_mfma_f32_16x16x32_bf16 v[86:89], v[142:145], v[190:193], v[86:89]
	s_setprio 0
	s_setprio 1
	v_mfma_f32_16x16x32_bf16 v[82:85], v[146:149], v[162:165], v[82:85]
	v_mfma_f32_16x16x32_bf16 v[74:77], v[154:157], v[162:165], v[74:77]
	v_mfma_f32_16x16x32_bf16 v[70:73], v[146:149], v[166:169], v[70:73]
	v_mfma_f32_16x16x32_bf16 v[66:69], v[154:157], v[166:169], v[66:69]
	v_mfma_f32_16x16x32_bf16 v[62:65], v[146:149], v[178:181], v[62:65]
	v_mfma_f32_16x16x32_bf16 v[58:61], v[154:157], v[178:181], v[58:61]
	v_mfma_f32_16x16x32_bf16 v[54:57], v[146:149], v[182:185], v[54:57]
	v_mfma_f32_16x16x32_bf16 v[50:53], v[154:157], v[182:185], v[50:53]
	v_mfma_f32_16x16x32_bf16 v[82:85], v[150:153], v[170:173], v[82:85]
	v_mfma_f32_16x16x32_bf16 v[74:77], v[158:161], v[170:173], v[74:77]
	v_mfma_f32_16x16x32_bf16 v[70:73], v[150:153], v[174:177], v[70:73]
	v_mfma_f32_16x16x32_bf16 v[66:69], v[158:161], v[174:177], v[66:69]
	v_mfma_f32_16x16x32_bf16 v[62:65], v[150:153], v[186:189], v[62:65]
	v_mfma_f32_16x16x32_bf16 v[58:61], v[158:161], v[186:189], v[58:61]
	v_mfma_f32_16x16x32_bf16 v[54:57], v[150:153], v[190:193], v[54:57]
	v_mfma_f32_16x16x32_bf16 v[50:53], v[158:161], v[190:193], v[50:53]
	s_setprio 0
	s_barrier
	s_mov_b32 m0, s29
	s_add_i32 s61, s60, 0x80
	ds_read_b128 v[162:165], v221 offset:49152
	ds_read_b128 v[166:169], v221 offset:51200
	ds_read_b128 v[170:173], v222 offset:49152
	ds_read_b128 v[174:177], v222 offset:51200
	ds_read_b128 v[178:181], v221 offset:53248
	ds_read_b128 v[182:185], v221 offset:55296
	ds_read_b128 v[186:189], v222 offset:53248
	ds_read_b128 v[190:193], v222 offset:55296
	buffer_load_dwordx4 v208, s[4:7], s61 offen lds
	s_mov_b32 m0, s30
	s_add_i32 s60, s60, 0x40080
	buffer_load_dwordx4 v210, s[4:7], s61 offen lds
	s_mov_b32 m0, s35
	s_nop 0
	buffer_load_dwordx4 v208, s[4:7], s60 offen lds
	s_mov_b32 m0, s36
	s_nop 0
	buffer_load_dwordx4 v210, s[4:7], s60 offen lds
	s_waitcnt vmcnt(6)
	s_waitcnt lgkmcnt(0)
	s_barrier
	s_setprio 1
	s_waitcnt lgkmcnt(7)
	v_mfma_f32_16x16x32_bf16 v[78:81], v[130:133], v[162:165], v[78:81]
	v_mfma_f32_16x16x32_bf16 v[46:49], v[138:141], v[162:165], v[46:49]
	s_waitcnt lgkmcnt(6)
	s_mov_b32 m0, s31
	s_nop 0
	buffer_load_dwordx4 v207, s[4:7], s59 offen lds
	v_mfma_f32_16x16x32_bf16 v[42:45], v[130:133], v[166:169], v[42:45]
	v_mfma_f32_16x16x32_bf16 v[38:41], v[138:141], v[166:169], v[38:41]
	s_waitcnt lgkmcnt(3)
	v_mfma_f32_16x16x32_bf16 v[34:37], v[130:133], v[178:181], v[34:37]
	v_mfma_f32_16x16x32_bf16 v[30:33], v[138:141], v[178:181], v[30:33]
	s_waitcnt lgkmcnt(2)
	s_mov_b32 m0, s34
	s_nop 0
	buffer_load_dwordx4 v209, s[4:7], s59 offen lds
	v_mfma_f32_16x16x32_bf16 v[26:29], v[130:133], v[182:185], v[26:29]
	v_mfma_f32_16x16x32_bf16 v[22:25], v[138:141], v[182:185], v[22:25]
	v_mfma_f32_16x16x32_bf16 v[78:81], v[134:137], v[170:173], v[78:81]
	v_mfma_f32_16x16x32_bf16 v[46:49], v[142:145], v[170:173], v[46:49]
	v_mfma_f32_16x16x32_bf16 v[42:45], v[134:137], v[174:177], v[42:45]
	v_mfma_f32_16x16x32_bf16 v[38:41], v[142:145], v[174:177], v[38:41]
	s_waitcnt lgkmcnt(1)
	v_mfma_f32_16x16x32_bf16 v[34:37], v[134:137], v[186:189], v[34:37]
	v_mfma_f32_16x16x32_bf16 v[30:33], v[142:145], v[186:189], v[30:33]
	s_waitcnt lgkmcnt(0)
	v_mfma_f32_16x16x32_bf16 v[26:29], v[134:137], v[190:193], v[26:29]
	v_mfma_f32_16x16x32_bf16 v[22:25], v[142:145], v[190:193], v[22:25]
	s_setprio 0
	s_setprio 1
	v_mfma_f32_16x16x32_bf16 v[18:21], v[146:149], v[162:165], v[18:21]
	v_mfma_f32_16x16x32_bf16 v[14:17], v[154:157], v[162:165], v[14:17]
	v_mfma_f32_16x16x32_bf16 v[10:13], v[146:149], v[166:169], v[10:13]
	v_mfma_f32_16x16x32_bf16 v[6:9], v[154:157], v[166:169], v[6:9]
	v_mfma_f32_16x16x32_bf16 v[2:5], v[146:149], v[178:181], v[2:5]
	v_mfma_f32_16x16x32_bf16 v[126:129], v[154:157], v[178:181], v[126:129]
	v_mfma_f32_16x16x32_bf16 v[122:125], v[146:149], v[182:185], v[122:125]
	v_mfma_f32_16x16x32_bf16 v[118:121], v[154:157], v[182:185], v[118:121]
	v_mfma_f32_16x16x32_bf16 v[18:21], v[150:153], v[170:173], v[18:21]
	v_mfma_f32_16x16x32_bf16 v[14:17], v[158:161], v[170:173], v[14:17]
	v_mfma_f32_16x16x32_bf16 v[10:13], v[150:153], v[174:177], v[10:13]
	v_mfma_f32_16x16x32_bf16 v[6:9], v[158:161], v[174:177], v[6:9]
	v_mfma_f32_16x16x32_bf16 v[2:5], v[150:153], v[186:189], v[2:5]
	v_mfma_f32_16x16x32_bf16 v[126:129], v[158:161], v[186:189], v[126:129]
	v_mfma_f32_16x16x32_bf16 v[122:125], v[150:153], v[190:193], v[122:125]
	v_mfma_f32_16x16x32_bf16 v[118:121], v[158:161], v[190:193], v[118:121]
	s_setprio 0
	s_barrier
	s_add_i32 s58, s58, 2
	s_addk_i32 s33, 0x100
	s_addk_i32 s57, 0x100
	s_cmp_gt_u32 s58, 13
	s_cbranch_scc0 .LBB0_233
	s_and_b64 vcc, exec, s[16:17]
	s_cbranch_vccz .LBB0_236
	s_barrier

.LBB0_841:
	ds_read_b128 v[130:133], v240
	ds_read_b128 v[134:137], v241
	ds_read_b128 v[138:141], v242
	ds_read_b128 v[142:145], v243
	ds_read_b128 v[146:149], v244
	ds_read_b128 v[150:153], v245
	ds_read_b128 v[154:157], v246
	ds_read_b128 v[158:161], v247
	s_add_i32 s8, s42, s5
	s_add_i32 s19, s34, s5
	s_add_i32 s18, s8, 0x800
	s_addk_i32 s19, 0x800
	s_cmp_eq_u32 s5, 0
	s_cselect_b32 s20, s0, s18
	s_cselect_b32 s19, s1, s19
	s_add_i32 s18, s20, 0x80
	s_add_i32 s21, s8, 0x40780
	s_mov_b32 s8, s70
	s_mov_b32 m0, s52
	ds_read_b128 v[162:165], v248
	ds_read_b128 v[166:169], v248 offset:2048
	ds_read_b128 v[170:173], v249
	ds_read_b128 v[174:177], v249 offset:2048
	ds_read_b128 v[178:181], v248 offset:4096
	ds_read_b128 v[182:185], v248 offset:6144
	ds_read_b128 v[186:189], v249 offset:4096
	ds_read_b128 v[190:193], v249 offset:6144
	buffer_load_dwordx4 v1, s[8:11], s21 offen lds
	s_mov_b32 m0, s53
	s_nop 0
	buffer_load_dwordx4 v234, s[8:11], s21 offen lds
	s_waitcnt vmcnt(8)
	s_waitcnt lgkmcnt(0)
	s_barrier
	s_setprio 1
	s_waitcnt lgkmcnt(7)
	v_mfma_f32_16x16x32_bf16 v[74:77], v[130:133], v[162:165], v[74:77]
	v_mfma_f32_16x16x32_bf16 v[70:73], v[138:141], v[162:165], v[70:73]
	s_waitcnt lgkmcnt(6)
	v_mfma_f32_16x16x32_bf16 v[66:69], v[130:133], v[166:169], v[66:69]
	v_mfma_f32_16x16x32_bf16 v[82:85], v[138:141], v[166:169], v[82:85]
	s_waitcnt lgkmcnt(3)
	v_mfma_f32_16x16x32_bf16 v[78:81], v[130:133], v[178:181], v[78:81]
	v_mfma_f32_16x16x32_bf16 v[90:93], v[138:141], v[178:181], v[90:93]
	s_waitcnt lgkmcnt(2)
	v_mfma_f32_16x16x32_bf16 v[86:89], v[130:133], v[182:185], v[86:89]
	v_mfma_f32_16x16x32_bf16 v[102:105], v[138:141], v[182:185], v[102:105]
	v_mfma_f32_16x16x32_bf16 v[74:77], v[134:137], v[170:173], v[74:77]
	v_mfma_f32_16x16x32_bf16 v[70:73], v[142:145], v[170:173], v[70:73]
	v_mfma_f32_16x16x32_bf16 v[66:69], v[134:137], v[174:177], v[66:69]
	v_mfma_f32_16x16x32_bf16 v[82:85], v[142:145], v[174:177], v[82:85]
	s_waitcnt lgkmcnt(1)
	v_mfma_f32_16x16x32_bf16 v[78:81], v[134:137], v[186:189], v[78:81]
	v_mfma_f32_16x16x32_bf16 v[90:93], v[142:145], v[186:189], v[90:93]
	s_waitcnt lgkmcnt(0)
	v_mfma_f32_16x16x32_bf16 v[86:89], v[134:137], v[190:193], v[86:89]
	v_mfma_f32_16x16x32_bf16 v[102:105], v[142:145], v[190:193], v[102:105]
	s_setprio 0
	s_setprio 1
	v_mfma_f32_16x16x32_bf16 v[98:101], v[146:149], v[162:165], v[98:101]
	v_mfma_f32_16x16x32_bf16 v[94:97], v[154:157], v[162:165], v[94:97]
	v_mfma_f32_16x16x32_bf16 v[106:109], v[146:149], v[166:169], v[106:109]
	v_mfma_f32_16x16x32_bf16 v[110:113], v[154:157], v[166:169], v[110:113]
	v_mfma_f32_16x16x32_bf16 v[114:117], v[146:149], v[178:181], v[114:117]
	v_mfma_f32_16x16x32_bf16 v[118:121], v[154:157], v[178:181], v[118:121]
	v_mfma_f32_16x16x32_bf16 v[122:125], v[146:149], v[182:185], v[122:125]
	v_mfma_f32_16x16x32_bf16 v[126:129], v[154:157], v[182:185], v[126:129]
	v_mfma_f32_16x16x32_bf16 v[98:101], v[150:153], v[170:173], v[98:101]
	v_mfma_f32_16x16x32_bf16 v[94:97], v[158:161], v[170:173], v[94:97]
	v_mfma_f32_16x16x32_bf16 v[106:109], v[150:153], v[174:177], v[106:109]
	v_mfma_f32_16x16x32_bf16 v[110:113], v[158:161], v[174:177], v[110:113]
	v_mfma_f32_16x16x32_bf16 v[114:117], v[150:153], v[186:189], v[114:117]
	v_mfma_f32_16x16x32_bf16 v[118:121], v[158:161], v[186:189], v[118:121]
	v_mfma_f32_16x16x32_bf16 v[122:125], v[150:153], v[190:193], v[122:125]
	v_mfma_f32_16x16x32_bf16 v[126:129], v[158:161], v[190:193], v[126:129]
	s_setprio 0
	s_barrier
	s_mov_b32 m0, s29
	ds_read_b128 v[162:165], v248 offset:16384
	ds_read_b128 v[166:169], v248 offset:18432
	ds_read_b128 v[170:173], v249 offset:16384
	ds_read_b128 v[174:177], v249 offset:18432
	ds_read_b128 v[178:181], v248 offset:20480
	ds_read_b128 v[182:185], v248 offset:22528
	ds_read_b128 v[186:189], v249 offset:20480
	ds_read_b128 v[190:193], v249 offset:22528
	buffer_load_dwordx4 v233, s[8:11], s19 offen lds
	s_mov_b32 m0, s30
	s_add_i32 s21, s19, 0x40000
	buffer_load_dwordx4 v235, s[8:11], s19 offen lds
	s_mov_b32 m0, s31
	s_nop 0
	buffer_load_dwordx4 v233, s[8:11], s21 offen lds
	s_mov_b32 m0, s35
	s_nop 0
	buffer_load_dwordx4 v235, s[8:11], s21 offen lds
	s_waitcnt vmcnt(6)
	s_waitcnt lgkmcnt(0)
	s_barrier
	s_setprio 1
	s_waitcnt lgkmcnt(7)
	v_mfma_f32_16x16x32_bf16 v[10:13], v[130:133], v[162:165], v[10:13]
	v_mfma_f32_16x16x32_bf16 v[6:9], v[138:141], v[162:165], v[6:9]
	s_waitcnt lgkmcnt(6)
	s_mov_b32 m0, s28
	s_nop 0
	buffer_load_dwordx4 v1, s[8:11], s20 offen lds
	v_mfma_f32_16x16x32_bf16 v[2:5], v[130:133], v[166:169], v[2:5]
	v_mfma_f32_16x16x32_bf16 v[18:21], v[138:141], v[166:169], v[18:21]
	s_waitcnt lgkmcnt(3)
	v_mfma_f32_16x16x32_bf16 v[14:17], v[130:133], v[178:181], v[14:17]
	v_mfma_f32_16x16x32_bf16 v[26:29], v[138:141], v[178:181], v[26:29]
	s_waitcnt lgkmcnt(2)
	s_mov_b32 m0, s38
	s_nop 0
	buffer_load_dwordx4 v234, s[8:11], s20 offen lds
	v_mfma_f32_16x16x32_bf16 v[22:25], v[130:133], v[182:185], v[22:25]
	v_mfma_f32_16x16x32_bf16 v[38:41], v[138:141], v[182:185], v[38:41]
	v_mfma_f32_16x16x32_bf16 v[10:13], v[134:137], v[170:173], v[10:13]
	v_mfma_f32_16x16x32_bf16 v[6:9], v[142:145], v[170:173], v[6:9]
	v_mfma_f32_16x16x32_bf16 v[2:5], v[134:137], v[174:177], v[2:5]
	v_mfma_f32_16x16x32_bf16 v[18:21], v[142:145], v[174:177], v[18:21]
	s_waitcnt lgkmcnt(1)
	v_mfma_f32_16x16x32_bf16 v[14:17], v[134:137], v[186:189], v[14:17]
	v_mfma_f32_16x16x32_bf16 v[26:29], v[142:145], v[186:189], v[26:29]
	s_waitcnt lgkmcnt(0)
	v_mfma_f32_16x16x32_bf16 v[22:25], v[134:137], v[190:193], v[22:25]
	v_mfma_f32_16x16x32_bf16 v[38:41], v[142:145], v[190:193], v[38:41]
	s_setprio 0
	s_setprio 1
	v_mfma_f32_16x16x32_bf16 v[34:37], v[146:149], v[162:165], v[34:37]
	v_mfma_f32_16x16x32_bf16 v[30:33], v[154:157], v[162:165], v[30:33]
	v_mfma_f32_16x16x32_bf16 v[42:45], v[146:149], v[166:169], v[42:45]
	v_mfma_f32_16x16x32_bf16 v[46:49], v[154:157], v[166:169], v[46:49]
	v_mfma_f32_16x16x32_bf16 v[50:53], v[146:149], v[178:181], v[50:53]
	v_mfma_f32_16x16x32_bf16 v[54:57], v[154:157], v[178:181], v[54:57]
	v_mfma_f32_16x16x32_bf16 v[58:61], v[146:149], v[182:185], v[58:61]
	v_mfma_f32_16x16x32_bf16 v[62:65], v[154:157], v[182:185], v[62:65]
	v_mfma_f32_16x16x32_bf16 v[34:37], v[150:153], v[170:173], v[34:37]
	v_mfma_f32_16x16x32_bf16 v[30:33], v[158:161], v[170:173], v[30:33]
	v_mfma_f32_16x16x32_bf16 v[42:45], v[150:153], v[174:177], v[42:45]
	v_mfma_f32_16x16x32_bf16 v[46:49], v[158:161], v[174:177], v[46:49]
	v_mfma_f32_16x16x32_bf16 v[50:53], v[150:153], v[186:189], v[50:53]
	v_mfma_f32_16x16x32_bf16 v[54:57], v[158:161], v[186:189], v[54:57]
	v_mfma_f32_16x16x32_bf16 v[58:61], v[150:153], v[190:193], v[58:61]
	v_mfma_f32_16x16x32_bf16 v[62:65], v[158:161], v[190:193], v[62:65]
	s_setprio 0
	s_barrier
	ds_read_b128 v[130:133], v194
	ds_read_b128 v[134:137], v195
	ds_read_b128 v[138:141], v196
	ds_read_b128 v[142:145], v197
	ds_read_b128 v[146:149], v198
	ds_read_b128 v[150:153], v199
	ds_read_b128 v[154:157], v200
	ds_read_b128 v[158:161], v201
	s_add_i32 s20, s20, 0x40000
	s_mov_b32 m0, s39
	ds_read_b128 v[162:165], v248 offset:32768
	ds_read_b128 v[166:169], v248 offset:34816
	ds_read_b128 v[170:173], v249 offset:32768
	ds_read_b128 v[174:177], v249 offset:34816
	ds_read_b128 v[178:181], v248 offset:36864
	ds_read_b128 v[182:185], v248 offset:38912
	ds_read_b128 v[186:189], v249 offset:36864
	ds_read_b128 v[190:193], v249 offset:38912
	buffer_load_dwordx4 v1, s[8:11], s20 offen lds
	s_mov_b32 m0, s41
	s_nop 0
	buffer_load_dwordx4 v234, s[8:11], s20 offen lds
	s_waitcnt vmcnt(8)
	s_waitcnt lgkmcnt(0)
	s_barrier
	s_setprio 1
	s_waitcnt lgkmcnt(7)
	v_mfma_f32_16x16x32_bf16 v[74:77], v[130:133], v[162:165], v[74:77]
	v_mfma_f32_16x16x32_bf16 v[70:73], v[138:141], v[162:165], v[70:73]
	s_waitcnt lgkmcnt(6)
	v_mfma_f32_16x16x32_bf16 v[66:69], v[130:133], v[166:169], v[66:69]
	v_mfma_f32_16x16x32_bf16 v[82:85], v[138:141], v[166:169], v[82:85]
	s_waitcnt lgkmcnt(3)
	v_mfma_f32_16x16x32_bf16 v[78:81], v[130:133], v[178:181], v[78:81]
	v_mfma_f32_16x16x32_bf16 v[90:93], v[138:141], v[178:181], v[90:93]
	s_waitcnt lgkmcnt(2)
	v_mfma_f32_16x16x32_bf16 v[86:89], v[130:133], v[182:185], v[86:89]
	v_mfma_f32_16x16x32_bf16 v[102:105], v[138:141], v[182:185], v[102:105]
	v_mfma_f32_16x16x32_bf16 v[74:77], v[134:137], v[170:173], v[74:77]
	v_mfma_f32_16x16x32_bf16 v[70:73], v[142:145], v[170:173], v[70:73]
	v_mfma_f32_16x16x32_bf16 v[66:69], v[134:137], v[174:177], v[66:69]
	v_mfma_f32_16x16x32_bf16 v[82:85], v[142:145], v[174:177], v[82:85]
	s_waitcnt lgkmcnt(1)
	v_mfma_f32_16x16x32_bf16 v[78:81], v[134:137], v[186:189], v[78:81]
	v_mfma_f32_16x16x32_bf16 v[90:93], v[142:145], v[186:189], v[90:93]
	s_waitcnt lgkmcnt(0)
	v_mfma_f32_16x16x32_bf16 v[86:89], v[134:137], v[190:193], v[86:89]
	v_mfma_f32_16x16x32_bf16 v[102:105], v[142:145], v[190:193], v[102:105]
	s_setprio 0
	s_setprio 1
	v_mfma_f32_16x16x32_bf16 v[98:101], v[146:149], v[162:165], v[98:101]
	v_mfma_f32_16x16x32_bf16 v[94:97], v[154:157], v[162:165], v[94:97]
	v_mfma_f32_16x16x32_bf16 v[106:109], v[146:149], v[166:169], v[106:109]
	v_mfma_f32_16x16x32_bf16 v[110:113], v[154:157], v[166:169], v[110:113]
	v_mfma_f32_16x16x32_bf16 v[114:117], v[146:149], v[178:181], v[114:117]
	v_mfma_f32_16x16x32_bf16 v[118:121], v[154:157], v[178:181], v[118:121]
	v_mfma_f32_16x16x32_bf16 v[122:125], v[146:149], v[182:185], v[122:125]
	v_mfma_f32_16x16x32_bf16 v[126:129], v[154:157], v[182:185], v[126:129]
	v_mfma_f32_16x16x32_bf16 v[98:101], v[150:153], v[170:173], v[98:101]
	v_mfma_f32_16x16x32_bf16 v[94:97], v[158:161], v[170:173], v[94:97]
	v_mfma_f32_16x16x32_bf16 v[106:109], v[150:153], v[174:177], v[106:109]
	v_mfma_f32_16x16x32_bf16 v[110:113], v[158:161], v[174:177], v[110:113]
	v_mfma_f32_16x16x32_bf16 v[114:117], v[150:153], v[186:189], v[114:117]
	v_mfma_f32_16x16x32_bf16 v[118:121], v[158:161], v[186:189], v[118:121]
	v_mfma_f32_16x16x32_bf16 v[122:125], v[150:153], v[190:193], v[122:125]
	v_mfma_f32_16x16x32_bf16 v[126:129], v[158:161], v[190:193], v[126:129]
	s_setprio 0
	s_barrier
	s_mov_b32 m0, s44
	s_add_i32 s20, s19, 0x80
	ds_read_b128 v[162:165], v248 offset:49152
	ds_read_b128 v[166:169], v248 offset:51200
	ds_read_b128 v[170:173], v249 offset:49152
	ds_read_b128 v[174:177], v249 offset:51200
	ds_read_b128 v[178:181], v248 offset:53248
	ds_read_b128 v[182:185], v248 offset:55296
	ds_read_b128 v[186:189], v249 offset:53248
	ds_read_b128 v[190:193], v249 offset:55296
	buffer_load_dwordx4 v233, s[8:11], s20 offen lds
	s_mov_b32 m0, s45
	s_add_i32 s19, s19, 0x40080
	buffer_load_dwordx4 v235, s[8:11], s20 offen lds
	s_mov_b32 m0, s48
	s_nop 0
	buffer_load_dwordx4 v233, s[8:11], s19 offen lds
	s_mov_b32 m0, s49
	s_nop 0
	buffer_load_dwordx4 v235, s[8:11], s19 offen lds
	s_waitcnt vmcnt(6)
	s_waitcnt lgkmcnt(0)
	s_barrier
	s_setprio 1
	s_waitcnt lgkmcnt(7)
	v_mfma_f32_16x16x32_bf16 v[10:13], v[130:133], v[162:165], v[10:13]
	v_mfma_f32_16x16x32_bf16 v[6:9], v[138:141], v[162:165], v[6:9]
	s_waitcnt lgkmcnt(6)
	s_mov_b32 m0, s46
	s_nop 0
	buffer_load_dwordx4 v1, s[8:11], s18 offen lds
	v_mfma_f32_16x16x32_bf16 v[2:5], v[130:133], v[166:169], v[2:5]
	v_mfma_f32_16x16x32_bf16 v[18:21], v[138:141], v[166:169], v[18:21]
	s_waitcnt lgkmcnt(3)
	v_mfma_f32_16x16x32_bf16 v[14:17], v[130:133], v[178:181], v[14:17]
	v_mfma_f32_16x16x32_bf16 v[26:29], v[138:141], v[178:181], v[26:29]
	s_waitcnt lgkmcnt(2)
	s_mov_b32 m0, s47
	s_nop 0
	buffer_load_dwordx4 v234, s[8:11], s18 offen lds
	v_mfma_f32_16x16x32_bf16 v[22:25], v[130:133], v[182:185], v[22:25]
	v_mfma_f32_16x16x32_bf16 v[38:41], v[138:141], v[182:185], v[38:41]
	v_mfma_f32_16x16x32_bf16 v[10:13], v[134:137], v[170:173], v[10:13]
	v_mfma_f32_16x16x32_bf16 v[6:9], v[142:145], v[170:173], v[6:9]
	v_mfma_f32_16x16x32_bf16 v[2:5], v[134:137], v[174:177], v[2:5]
	v_mfma_f32_16x16x32_bf16 v[18:21], v[142:145], v[174:177], v[18:21]
	s_waitcnt lgkmcnt(1)
	v_mfma_f32_16x16x32_bf16 v[14:17], v[134:137], v[186:189], v[14:17]
	v_mfma_f32_16x16x32_bf16 v[26:29], v[142:145], v[186:189], v[26:29]
	s_waitcnt lgkmcnt(0)
	v_mfma_f32_16x16x32_bf16 v[22:25], v[134:137], v[190:193], v[22:25]
	v_mfma_f32_16x16x32_bf16 v[38:41], v[142:145], v[190:193], v[38:41]
	s_setprio 0
	s_setprio 1
	v_mfma_f32_16x16x32_bf16 v[34:37], v[146:149], v[162:165], v[34:37]
	v_mfma_f32_16x16x32_bf16 v[30:33], v[154:157], v[162:165], v[30:33]
	v_mfma_f32_16x16x32_bf16 v[42:45], v[146:149], v[166:169], v[42:45]
	v_mfma_f32_16x16x32_bf16 v[46:49], v[154:157], v[166:169], v[46:49]
	v_mfma_f32_16x16x32_bf16 v[50:53], v[146:149], v[178:181], v[50:53]
	v_mfma_f32_16x16x32_bf16 v[54:57], v[154:157], v[178:181], v[54:57]
	v_mfma_f32_16x16x32_bf16 v[58:61], v[146:149], v[182:185], v[58:61]
	v_mfma_f32_16x16x32_bf16 v[62:65], v[154:157], v[182:185], v[62:65]
	v_mfma_f32_16x16x32_bf16 v[34:37], v[150:153], v[170:173], v[34:37]
	v_mfma_f32_16x16x32_bf16 v[30:33], v[158:161], v[170:173], v[30:33]
	v_mfma_f32_16x16x32_bf16 v[42:45], v[150:153], v[174:177], v[42:45]
	v_mfma_f32_16x16x32_bf16 v[46:49], v[158:161], v[174:177], v[46:49]
	v_mfma_f32_16x16x32_bf16 v[50:53], v[150:153], v[186:189], v[50:53]
	v_mfma_f32_16x16x32_bf16 v[54:57], v[158:161], v[186:189], v[54:57]
	v_mfma_f32_16x16x32_bf16 v[58:61], v[150:153], v[190:193], v[58:61]
	v_mfma_f32_16x16x32_bf16 v[62:65], v[158:161], v[190:193], v[62:65]
	s_setprio 0
	s_barrier
	s_add_i32 s4, s4, 2
	s_addk_i32 s5, 0x100
	s_cmp_gt_u32 s4, 13
	s_cbranch_scc0 .LBB0_841
	s_and_b64 vcc, exec, s[16:17]
	s_cbranch_vccz .LBB0_844
	s_barrier

.LBB0_1122:
	ds_read_b128 v[130:133], v240
	ds_read_b128 v[134:137], v241
	ds_read_b128 v[138:141], v242
	ds_read_b128 v[142:145], v243
	ds_read_b128 v[146:149], v244
	ds_read_b128 v[150:153], v245
	ds_read_b128 v[154:157], v246
	ds_read_b128 v[158:161], v247
	s_add_i32 s8, s31, s53
	s_add_i32 s55, s26, s53
	s_add_i32 s54, s8, 0x800
	s_addk_i32 s55, 0x800
	s_cmp_eq_u32 s53, 0
	s_cselect_b32 s56, s4, s54
	s_cselect_b32 s55, s5, s55
	s_add_i32 s54, s56, 0x80
	s_add_i32 s57, s8, 0x40780
	s_mov_b32 s8, s70
	s_mov_b32 m0, s44
	ds_read_b128 v[162:165], v248
	ds_read_b128 v[166:169], v248 offset:2048
	ds_read_b128 v[170:173], v249
	ds_read_b128 v[174:177], v249 offset:2048
	ds_read_b128 v[178:181], v248 offset:4096
	ds_read_b128 v[182:185], v248 offset:6144
	ds_read_b128 v[186:189], v249 offset:4096
	ds_read_b128 v[190:193], v249 offset:6144
	buffer_load_dwordx4 v1, s[8:11], s57 offen lds
	s_mov_b32 m0, s45
	s_nop 0
	buffer_load_dwordx4 v234, s[8:11], s57 offen lds
	s_waitcnt vmcnt(8)
	s_waitcnt lgkmcnt(0)
	s_barrier
	s_setprio 1
	s_waitcnt lgkmcnt(7)
	v_mfma_f32_16x16x32_bf16 v[126:129], v[130:133], v[162:165], v[126:129]
	v_mfma_f32_16x16x32_bf16 v[122:125], v[138:141], v[162:165], v[122:125]
	s_waitcnt lgkmcnt(6)
	v_mfma_f32_16x16x32_bf16 v[118:121], v[130:133], v[166:169], v[118:121]
	v_mfma_f32_16x16x32_bf16 v[114:117], v[138:141], v[166:169], v[114:117]
	s_waitcnt lgkmcnt(3)
	v_mfma_f32_16x16x32_bf16 v[110:113], v[130:133], v[178:181], v[110:113]
	v_mfma_f32_16x16x32_bf16 v[106:109], v[138:141], v[178:181], v[106:109]
	s_waitcnt lgkmcnt(2)
	v_mfma_f32_16x16x32_bf16 v[102:105], v[130:133], v[182:185], v[102:105]
	v_mfma_f32_16x16x32_bf16 v[98:101], v[138:141], v[182:185], v[98:101]
	v_mfma_f32_16x16x32_bf16 v[126:129], v[134:137], v[170:173], v[126:129]
	v_mfma_f32_16x16x32_bf16 v[122:125], v[142:145], v[170:173], v[122:125]
	v_mfma_f32_16x16x32_bf16 v[118:121], v[134:137], v[174:177], v[118:121]
	v_mfma_f32_16x16x32_bf16 v[114:117], v[142:145], v[174:177], v[114:117]
	s_waitcnt lgkmcnt(1)
	v_mfma_f32_16x16x32_bf16 v[110:113], v[134:137], v[186:189], v[110:113]
	v_mfma_f32_16x16x32_bf16 v[106:109], v[142:145], v[186:189], v[106:109]
	s_waitcnt lgkmcnt(0)
	v_mfma_f32_16x16x32_bf16 v[102:105], v[134:137], v[190:193], v[102:105]
	v_mfma_f32_16x16x32_bf16 v[98:101], v[142:145], v[190:193], v[98:101]
	s_setprio 0
	s_setprio 1
	v_mfma_f32_16x16x32_bf16 v[94:97], v[146:149], v[162:165], v[94:97]
	v_mfma_f32_16x16x32_bf16 v[90:93], v[154:157], v[162:165], v[90:93]
	v_mfma_f32_16x16x32_bf16 v[86:89], v[146:149], v[166:169], v[86:89]
	v_mfma_f32_16x16x32_bf16 v[82:85], v[154:157], v[166:169], v[82:85]
	v_mfma_f32_16x16x32_bf16 v[78:81], v[146:149], v[178:181], v[78:81]
	v_mfma_f32_16x16x32_bf16 v[74:77], v[154:157], v[178:181], v[74:77]
	v_mfma_f32_16x16x32_bf16 v[70:73], v[146:149], v[182:185], v[70:73]
	v_mfma_f32_16x16x32_bf16 v[66:69], v[154:157], v[182:185], v[66:69]
	v_mfma_f32_16x16x32_bf16 v[94:97], v[150:153], v[170:173], v[94:97]
	v_mfma_f32_16x16x32_bf16 v[90:93], v[158:161], v[170:173], v[90:93]
	v_mfma_f32_16x16x32_bf16 v[86:89], v[150:153], v[174:177], v[86:89]
	v_mfma_f32_16x16x32_bf16 v[82:85], v[158:161], v[174:177], v[82:85]
	v_mfma_f32_16x16x32_bf16 v[78:81], v[150:153], v[186:189], v[78:81]
	v_mfma_f32_16x16x32_bf16 v[74:77], v[158:161], v[186:189], v[74:77]
	v_mfma_f32_16x16x32_bf16 v[70:73], v[150:153], v[190:193], v[70:73]
	v_mfma_f32_16x16x32_bf16 v[66:69], v[158:161], v[190:193], v[66:69]
	s_setprio 0
	s_barrier
	s_mov_b32 m0, s23
	ds_read_b128 v[162:165], v248 offset:16384
	ds_read_b128 v[166:169], v248 offset:18432
	ds_read_b128 v[170:173], v249 offset:16384
	ds_read_b128 v[174:177], v249 offset:18432
	ds_read_b128 v[178:181], v248 offset:20480
	ds_read_b128 v[182:185], v248 offset:22528
	ds_read_b128 v[186:189], v249 offset:20480
	ds_read_b128 v[190:193], v249 offset:22528
	buffer_load_dwordx4 v233, s[8:11], s55 offen lds
	s_mov_b32 m0, s24
	s_add_i32 s57, s55, 0x40000
	buffer_load_dwordx4 v235, s[8:11], s55 offen lds
	s_mov_b32 m0, s25
	s_nop 0
	buffer_load_dwordx4 v233, s[8:11], s57 offen lds
	s_mov_b32 m0, s27
	s_nop 0
	buffer_load_dwordx4 v235, s[8:11], s57 offen lds
	s_waitcnt vmcnt(6)
	s_waitcnt lgkmcnt(0)
	s_barrier
	s_setprio 1
	s_waitcnt lgkmcnt(7)
	v_mfma_f32_16x16x32_bf16 v[62:65], v[130:133], v[162:165], v[62:65]
	v_mfma_f32_16x16x32_bf16 v[58:61], v[138:141], v[162:165], v[58:61]
	s_waitcnt lgkmcnt(6)
	s_mov_b32 m0, s22
	s_nop 0
	buffer_load_dwordx4 v1, s[8:11], s56 offen lds
	v_mfma_f32_16x16x32_bf16 v[54:57], v[130:133], v[166:169], v[54:57]
	v_mfma_f32_16x16x32_bf16 v[50:53], v[138:141], v[166:169], v[50:53]
	s_waitcnt lgkmcnt(3)
	v_mfma_f32_16x16x32_bf16 v[46:49], v[130:133], v[178:181], v[46:49]
	v_mfma_f32_16x16x32_bf16 v[42:45], v[138:141], v[178:181], v[42:45]
	s_waitcnt lgkmcnt(2)
	s_mov_b32 m0, s28
	s_nop 0
	buffer_load_dwordx4 v234, s[8:11], s56 offen lds
	v_mfma_f32_16x16x32_bf16 v[38:41], v[130:133], v[182:185], v[38:41]
	v_mfma_f32_16x16x32_bf16 v[34:37], v[138:141], v[182:185], v[34:37]
	v_mfma_f32_16x16x32_bf16 v[62:65], v[134:137], v[170:173], v[62:65]
	v_mfma_f32_16x16x32_bf16 v[58:61], v[142:145], v[170:173], v[58:61]
	v_mfma_f32_16x16x32_bf16 v[54:57], v[134:137], v[174:177], v[54:57]
	v_mfma_f32_16x16x32_bf16 v[50:53], v[142:145], v[174:177], v[50:53]
	s_waitcnt lgkmcnt(1)
	v_mfma_f32_16x16x32_bf16 v[46:49], v[134:137], v[186:189], v[46:49]
	v_mfma_f32_16x16x32_bf16 v[42:45], v[142:145], v[186:189], v[42:45]
	s_waitcnt lgkmcnt(0)
	v_mfma_f32_16x16x32_bf16 v[38:41], v[134:137], v[190:193], v[38:41]
	v_mfma_f32_16x16x32_bf16 v[34:37], v[142:145], v[190:193], v[34:37]
	s_setprio 0
	s_setprio 1
	v_mfma_f32_16x16x32_bf16 v[30:33], v[146:149], v[162:165], v[30:33]
	v_mfma_f32_16x16x32_bf16 v[26:29], v[154:157], v[162:165], v[26:29]
	v_mfma_f32_16x16x32_bf16 v[22:25], v[146:149], v[166:169], v[22:25]
	v_mfma_f32_16x16x32_bf16 v[18:21], v[154:157], v[166:169], v[18:21]
	v_mfma_f32_16x16x32_bf16 v[14:17], v[146:149], v[178:181], v[14:17]
	v_mfma_f32_16x16x32_bf16 v[10:13], v[154:157], v[178:181], v[10:13]
	v_mfma_f32_16x16x32_bf16 v[6:9], v[146:149], v[182:185], v[6:9]
	v_mfma_f32_16x16x32_bf16 v[2:5], v[154:157], v[182:185], v[2:5]
	v_mfma_f32_16x16x32_bf16 v[30:33], v[150:153], v[170:173], v[30:33]
	v_mfma_f32_16x16x32_bf16 v[26:29], v[158:161], v[170:173], v[26:29]
	v_mfma_f32_16x16x32_bf16 v[22:25], v[150:153], v[174:177], v[22:25]
	v_mfma_f32_16x16x32_bf16 v[18:21], v[158:161], v[174:177], v[18:21]
	v_mfma_f32_16x16x32_bf16 v[14:17], v[150:153], v[186:189], v[14:17]
	v_mfma_f32_16x16x32_bf16 v[10:13], v[158:161], v[186:189], v[10:13]
	v_mfma_f32_16x16x32_bf16 v[6:9], v[150:153], v[190:193], v[6:9]
	v_mfma_f32_16x16x32_bf16 v[2:5], v[158:161], v[190:193], v[2:5]
	s_setprio 0
	s_barrier
	ds_read_b128 v[130:133], v194
	ds_read_b128 v[134:137], v195
	ds_read_b128 v[138:141], v196
	ds_read_b128 v[142:145], v197
	ds_read_b128 v[146:149], v198
	ds_read_b128 v[150:153], v199
	ds_read_b128 v[154:157], v200
	ds_read_b128 v[158:161], v201
	s_add_i32 s56, s56, 0x40000
	s_mov_b32 m0, s29
	ds_read_b128 v[162:165], v248 offset:32768
	ds_read_b128 v[166:169], v248 offset:34816
	ds_read_b128 v[170:173], v249 offset:32768
	ds_read_b128 v[174:177], v249 offset:34816
	ds_read_b128 v[178:181], v248 offset:36864
	ds_read_b128 v[182:185], v248 offset:38912
	ds_read_b128 v[186:189], v249 offset:36864
	ds_read_b128 v[190:193], v249 offset:38912
	buffer_load_dwordx4 v1, s[8:11], s56 offen lds
	s_mov_b32 m0, s30
	s_nop 0
	buffer_load_dwordx4 v234, s[8:11], s56 offen lds
	s_waitcnt vmcnt(8)
	s_waitcnt lgkmcnt(0)
	s_barrier
	s_setprio 1
	s_waitcnt lgkmcnt(7)
	v_mfma_f32_16x16x32_bf16 v[126:129], v[130:133], v[162:165], v[126:129]
	v_mfma_f32_16x16x32_bf16 v[122:125], v[138:141], v[162:165], v[122:125]
	s_waitcnt lgkmcnt(6)
	v_mfma_f32_16x16x32_bf16 v[118:121], v[130:133], v[166:169], v[118:121]
	v_mfma_f32_16x16x32_bf16 v[114:117], v[138:141], v[166:169], v[114:117]
	s_waitcnt lgkmcnt(3)
	v_mfma_f32_16x16x32_bf16 v[110:113], v[130:133], v[178:181], v[110:113]
	v_mfma_f32_16x16x32_bf16 v[106:109], v[138:141], v[178:181], v[106:109]
	s_waitcnt lgkmcnt(2)
	v_mfma_f32_16x16x32_bf16 v[102:105], v[130:133], v[182:185], v[102:105]
	v_mfma_f32_16x16x32_bf16 v[98:101], v[138:141], v[182:185], v[98:101]
	v_mfma_f32_16x16x32_bf16 v[126:129], v[134:137], v[170:173], v[126:129]
	v_mfma_f32_16x16x32_bf16 v[122:125], v[142:145], v[170:173], v[122:125]
	v_mfma_f32_16x16x32_bf16 v[118:121], v[134:137], v[174:177], v[118:121]
	v_mfma_f32_16x16x32_bf16 v[114:117], v[142:145], v[174:177], v[114:117]
	s_waitcnt lgkmcnt(1)
	v_mfma_f32_16x16x32_bf16 v[110:113], v[134:137], v[186:189], v[110:113]
	v_mfma_f32_16x16x32_bf16 v[106:109], v[142:145], v[186:189], v[106:109]
	s_waitcnt lgkmcnt(0)
	v_mfma_f32_16x16x32_bf16 v[102:105], v[134:137], v[190:193], v[102:105]
	v_mfma_f32_16x16x32_bf16 v[98:101], v[142:145], v[190:193], v[98:101]
	s_setprio 0
	s_setprio 1
	v_mfma_f32_16x16x32_bf16 v[94:97], v[146:149], v[162:165], v[94:97]
	v_mfma_f32_16x16x32_bf16 v[90:93], v[154:157], v[162:165], v[90:93]
	v_mfma_f32_16x16x32_bf16 v[86:89], v[146:149], v[166:169], v[86:89]
	v_mfma_f32_16x16x32_bf16 v[82:85], v[154:157], v[166:169], v[82:85]
	v_mfma_f32_16x16x32_bf16 v[78:81], v[146:149], v[178:181], v[78:81]
	v_mfma_f32_16x16x32_bf16 v[74:77], v[154:157], v[178:181], v[74:77]
	v_mfma_f32_16x16x32_bf16 v[70:73], v[146:149], v[182:185], v[70:73]
	v_mfma_f32_16x16x32_bf16 v[66:69], v[154:157], v[182:185], v[66:69]
	v_mfma_f32_16x16x32_bf16 v[94:97], v[150:153], v[170:173], v[94:97]
	v_mfma_f32_16x16x32_bf16 v[90:93], v[158:161], v[170:173], v[90:93]
	v_mfma_f32_16x16x32_bf16 v[86:89], v[150:153], v[174:177], v[86:89]
	v_mfma_f32_16x16x32_bf16 v[82:85], v[158:161], v[174:177], v[82:85]
	v_mfma_f32_16x16x32_bf16 v[78:81], v[150:153], v[186:189], v[78:81]
	v_mfma_f32_16x16x32_bf16 v[74:77], v[158:161], v[186:189], v[74:77]
	v_mfma_f32_16x16x32_bf16 v[70:73], v[150:153], v[190:193], v[70:73]
	v_mfma_f32_16x16x32_bf16 v[66:69], v[158:161], v[190:193], v[66:69]
	s_setprio 0
	s_barrier
	s_mov_b32 m0, s35
	s_add_i32 s56, s55, 0x80
	ds_read_b128 v[162:165], v248 offset:49152
	ds_read_b128 v[166:169], v248 offset:51200
	ds_read_b128 v[170:173], v249 offset:49152
	ds_read_b128 v[174:177], v249 offset:51200
	ds_read_b128 v[178:181], v248 offset:53248
	ds_read_b128 v[182:185], v248 offset:55296
	ds_read_b128 v[186:189], v249 offset:53248
	ds_read_b128 v[190:193], v249 offset:55296
	buffer_load_dwordx4 v233, s[8:11], s56 offen lds
	s_mov_b32 m0, s36
	s_add_i32 s55, s55, 0x40080
	buffer_load_dwordx4 v235, s[8:11], s56 offen lds
	s_mov_b32 m0, s39
	s_nop 0
	buffer_load_dwordx4 v233, s[8:11], s55 offen lds
	s_mov_b32 m0, s41
	s_nop 0
	buffer_load_dwordx4 v235, s[8:11], s55 offen lds
	s_waitcnt vmcnt(6)
	s_waitcnt lgkmcnt(0)
	s_barrier
	s_setprio 1
	s_waitcnt lgkmcnt(7)
	v_mfma_f32_16x16x32_bf16 v[62:65], v[130:133], v[162:165], v[62:65]
	v_mfma_f32_16x16x32_bf16 v[58:61], v[138:141], v[162:165], v[58:61]
	s_waitcnt lgkmcnt(6)
	s_mov_b32 m0, s37
	s_nop 0
	buffer_load_dwordx4 v1, s[8:11], s54 offen lds
	v_mfma_f32_16x16x32_bf16 v[54:57], v[130:133], v[166:169], v[54:57]
	v_mfma_f32_16x16x32_bf16 v[50:53], v[138:141], v[166:169], v[50:53]
	s_waitcnt lgkmcnt(3)
	v_mfma_f32_16x16x32_bf16 v[46:49], v[130:133], v[178:181], v[46:49]
	v_mfma_f32_16x16x32_bf16 v[42:45], v[138:141], v[178:181], v[42:45]
	s_waitcnt lgkmcnt(2)
	s_mov_b32 m0, s38
	s_nop 0
	buffer_load_dwordx4 v234, s[8:11], s54 offen lds
	v_mfma_f32_16x16x32_bf16 v[38:41], v[130:133], v[182:185], v[38:41]
	v_mfma_f32_16x16x32_bf16 v[34:37], v[138:141], v[182:185], v[34:37]
	v_mfma_f32_16x16x32_bf16 v[62:65], v[134:137], v[170:173], v[62:65]
	v_mfma_f32_16x16x32_bf16 v[58:61], v[142:145], v[170:173], v[58:61]
	v_mfma_f32_16x16x32_bf16 v[54:57], v[134:137], v[174:177], v[54:57]
	v_mfma_f32_16x16x32_bf16 v[50:53], v[142:145], v[174:177], v[50:53]
	s_waitcnt lgkmcnt(1)
	v_mfma_f32_16x16x32_bf16 v[46:49], v[134:137], v[186:189], v[46:49]
	v_mfma_f32_16x16x32_bf16 v[42:45], v[142:145], v[186:189], v[42:45]
	s_waitcnt lgkmcnt(0)
	v_mfma_f32_16x16x32_bf16 v[38:41], v[134:137], v[190:193], v[38:41]
	v_mfma_f32_16x16x32_bf16 v[34:37], v[142:145], v[190:193], v[34:37]
	s_setprio 0
	s_setprio 1
	v_mfma_f32_16x16x32_bf16 v[30:33], v[146:149], v[162:165], v[30:33]
	v_mfma_f32_16x16x32_bf16 v[26:29], v[154:157], v[162:165], v[26:29]
	v_mfma_f32_16x16x32_bf16 v[22:25], v[146:149], v[166:169], v[22:25]
	v_mfma_f32_16x16x32_bf16 v[18:21], v[154:157], v[166:169], v[18:21]
	v_mfma_f32_16x16x32_bf16 v[14:17], v[146:149], v[178:181], v[14:17]
	v_mfma_f32_16x16x32_bf16 v[10:13], v[154:157], v[178:181], v[10:13]
	v_mfma_f32_16x16x32_bf16 v[6:9], v[146:149], v[182:185], v[6:9]
	v_mfma_f32_16x16x32_bf16 v[2:5], v[154:157], v[182:185], v[2:5]
	v_mfma_f32_16x16x32_bf16 v[30:33], v[150:153], v[170:173], v[30:33]
	v_mfma_f32_16x16x32_bf16 v[26:29], v[158:161], v[170:173], v[26:29]
	v_mfma_f32_16x16x32_bf16 v[22:25], v[150:153], v[174:177], v[22:25]
	v_mfma_f32_16x16x32_bf16 v[18:21], v[158:161], v[174:177], v[18:21]
	v_mfma_f32_16x16x32_bf16 v[14:17], v[150:153], v[186:189], v[14:17]
	v_mfma_f32_16x16x32_bf16 v[10:13], v[158:161], v[186:189], v[10:13]
	v_mfma_f32_16x16x32_bf16 v[6:9], v[150:153], v[190:193], v[6:9]
	v_mfma_f32_16x16x32_bf16 v[2:5], v[158:161], v[190:193], v[2:5]
	s_setprio 0
	s_barrier
	s_add_i32 s33, s33, 2
	s_addk_i32 s53, 0x100
	s_cmp_gt_u32 s33, 13
	s_cbranch_scc0 .LBB0_1122
	s_and_b64 vcc, exec, s[16:17]
	s_cbranch_vccz .LBB0_1125
	s_barrier

.LBB0_1251:
	ds_read_b128 v[130:133], v239
	ds_read_b128 v[134:137], v240
	ds_read_b128 v[138:141], v241
	ds_read_b128 v[142:145], v242
	ds_read_b128 v[146:149], v243
	ds_read_b128 v[150:153], v244
	ds_read_b128 v[154:157], v245
	ds_read_b128 v[158:161], v246
	s_add_i32 s8, s51, s5
	s_add_i32 s31, s46, s5
	s_add_i32 s30, s8, 0x2000
	s_addk_i32 s31, 0x2000
	s_cmp_eq_u32 s5, 0
	s_cselect_b32 s33, s0, s30
	s_cselect_b32 s31, s1, s31
	s_add_i32 s30, s33, 0x80
	s_add_i32 s34, s8, 0x101f80
	s_mov_b32 s8, s70
	s_mov_b32 m0, s61
	ds_read_b128 v[162:165], v247
	ds_read_b128 v[166:169], v247 offset:2048
	ds_read_b128 v[170:173], v248
	ds_read_b128 v[174:177], v248 offset:2048
	ds_read_b128 v[178:181], v247 offset:4096
	ds_read_b128 v[182:185], v247 offset:6144
	ds_read_b128 v[186:189], v248 offset:4096
	ds_read_b128 v[190:193], v248 offset:6144
	buffer_load_dwordx4 v230, s[8:11], s34 offen lds
	s_mov_b32 m0, s64
	s_nop 0
	buffer_load_dwordx4 v233, s[8:11], s34 offen lds
	s_waitcnt vmcnt(8)
	s_waitcnt lgkmcnt(0)
	s_barrier
	s_setprio 1
	s_waitcnt lgkmcnt(7)
	v_mfma_f32_16x16x32_bf16 v[74:77], v[130:133], v[162:165], v[74:77]
	v_mfma_f32_16x16x32_bf16 v[70:73], v[138:141], v[162:165], v[70:73]
	s_waitcnt lgkmcnt(6)
	v_mfma_f32_16x16x32_bf16 v[66:69], v[130:133], v[166:169], v[66:69]
	v_mfma_f32_16x16x32_bf16 v[82:85], v[138:141], v[166:169], v[82:85]
	s_waitcnt lgkmcnt(3)
	v_mfma_f32_16x16x32_bf16 v[78:81], v[130:133], v[178:181], v[78:81]
	v_mfma_f32_16x16x32_bf16 v[90:93], v[138:141], v[178:181], v[90:93]
	s_waitcnt lgkmcnt(2)
	v_mfma_f32_16x16x32_bf16 v[86:89], v[130:133], v[182:185], v[86:89]
	v_mfma_f32_16x16x32_bf16 v[102:105], v[138:141], v[182:185], v[102:105]
	v_mfma_f32_16x16x32_bf16 v[74:77], v[134:137], v[170:173], v[74:77]
	v_mfma_f32_16x16x32_bf16 v[70:73], v[142:145], v[170:173], v[70:73]
	v_mfma_f32_16x16x32_bf16 v[66:69], v[134:137], v[174:177], v[66:69]
	v_mfma_f32_16x16x32_bf16 v[82:85], v[142:145], v[174:177], v[82:85]
	s_waitcnt lgkmcnt(1)
	v_mfma_f32_16x16x32_bf16 v[78:81], v[134:137], v[186:189], v[78:81]
	v_mfma_f32_16x16x32_bf16 v[90:93], v[142:145], v[186:189], v[90:93]
	s_waitcnt lgkmcnt(0)
	v_mfma_f32_16x16x32_bf16 v[86:89], v[134:137], v[190:193], v[86:89]
	v_mfma_f32_16x16x32_bf16 v[102:105], v[142:145], v[190:193], v[102:105]
	s_setprio 0
	s_setprio 1
	v_mfma_f32_16x16x32_bf16 v[98:101], v[146:149], v[162:165], v[98:101]
	v_mfma_f32_16x16x32_bf16 v[94:97], v[154:157], v[162:165], v[94:97]
	v_mfma_f32_16x16x32_bf16 v[106:109], v[146:149], v[166:169], v[106:109]
	v_mfma_f32_16x16x32_bf16 v[110:113], v[154:157], v[166:169], v[110:113]
	v_mfma_f32_16x16x32_bf16 v[114:117], v[146:149], v[178:181], v[114:117]
	v_mfma_f32_16x16x32_bf16 v[118:121], v[154:157], v[178:181], v[118:121]
	v_mfma_f32_16x16x32_bf16 v[122:125], v[146:149], v[182:185], v[122:125]
	v_mfma_f32_16x16x32_bf16 v[126:129], v[154:157], v[182:185], v[126:129]
	v_mfma_f32_16x16x32_bf16 v[98:101], v[150:153], v[170:173], v[98:101]
	v_mfma_f32_16x16x32_bf16 v[94:97], v[158:161], v[170:173], v[94:97]
	v_mfma_f32_16x16x32_bf16 v[106:109], v[150:153], v[174:177], v[106:109]
	v_mfma_f32_16x16x32_bf16 v[110:113], v[158:161], v[174:177], v[110:113]
	v_mfma_f32_16x16x32_bf16 v[114:117], v[150:153], v[186:189], v[114:117]
	v_mfma_f32_16x16x32_bf16 v[118:121], v[158:161], v[186:189], v[118:121]
	v_mfma_f32_16x16x32_bf16 v[122:125], v[150:153], v[190:193], v[122:125]
	v_mfma_f32_16x16x32_bf16 v[126:129], v[158:161], v[190:193], v[126:129]
	s_setprio 0
	s_barrier
	s_mov_b32 m0, s43
	ds_read_b128 v[162:165], v247 offset:16384
	ds_read_b128 v[166:169], v247 offset:18432
	ds_read_b128 v[170:173], v248 offset:16384
	ds_read_b128 v[174:177], v248 offset:18432
	ds_read_b128 v[178:181], v247 offset:20480
	ds_read_b128 v[182:185], v247 offset:22528
	ds_read_b128 v[186:189], v248 offset:20480
	ds_read_b128 v[190:193], v248 offset:22528
	buffer_load_dwordx4 v231, s[8:11], s31 offen lds
	s_mov_b32 m0, s44
	s_add_i32 s34, s31, 0x100000
	buffer_load_dwordx4 v234, s[8:11], s31 offen lds
	s_mov_b32 m0, s45
	s_nop 0
	buffer_load_dwordx4 v231, s[8:11], s34 offen lds
	s_mov_b32 m0, s47
	s_nop 0
	buffer_load_dwordx4 v234, s[8:11], s34 offen lds
	s_waitcnt vmcnt(6)
	s_waitcnt lgkmcnt(0)
	s_barrier
	s_setprio 1
	s_waitcnt lgkmcnt(7)
	v_mfma_f32_16x16x32_bf16 v[10:13], v[130:133], v[162:165], v[10:13]
	v_mfma_f32_16x16x32_bf16 v[6:9], v[138:141], v[162:165], v[6:9]
	s_waitcnt lgkmcnt(6)
	s_mov_b32 m0, s42
	s_nop 0
	buffer_load_dwordx4 v230, s[8:11], s33 offen lds
	v_mfma_f32_16x16x32_bf16 v[0:3], v[130:133], v[166:169], v[2:5]
	v_mfma_f32_16x16x32_bf16 v[18:21], v[138:141], v[166:169], v[18:21]
	s_waitcnt lgkmcnt(3)
	v_mfma_f32_16x16x32_bf16 v[14:17], v[130:133], v[178:181], v[14:17]
	v_mfma_f32_16x16x32_bf16 v[26:29], v[138:141], v[178:181], v[26:29]
	s_waitcnt lgkmcnt(2)
	s_mov_b32 m0, s48
	s_nop 0
	buffer_load_dwordx4 v233, s[8:11], s33 offen lds
	v_mfma_f32_16x16x32_bf16 v[22:25], v[130:133], v[182:185], v[22:25]
	v_mfma_f32_16x16x32_bf16 v[38:41], v[138:141], v[182:185], v[38:41]
	v_mfma_f32_16x16x32_bf16 v[10:13], v[134:137], v[170:173], v[10:13]
	v_mfma_f32_16x16x32_bf16 v[6:9], v[142:145], v[170:173], v[6:9]
	v_mfma_f32_16x16x32_bf16 v[0:3], v[134:137], v[174:177], v[0:3]
	v_mfma_f32_16x16x32_bf16 v[18:21], v[142:145], v[174:177], v[18:21]
	s_waitcnt lgkmcnt(1)
	v_mfma_f32_16x16x32_bf16 v[14:17], v[134:137], v[186:189], v[14:17]
	v_mfma_f32_16x16x32_bf16 v[26:29], v[142:145], v[186:189], v[26:29]
	s_waitcnt lgkmcnt(0)
	v_mfma_f32_16x16x32_bf16 v[22:25], v[134:137], v[190:193], v[22:25]
	v_mfma_f32_16x16x32_bf16 v[38:41], v[142:145], v[190:193], v[38:41]
	s_setprio 0
	s_setprio 1
	v_mfma_f32_16x16x32_bf16 v[34:37], v[146:149], v[162:165], v[34:37]
	v_mfma_f32_16x16x32_bf16 v[30:33], v[154:157], v[162:165], v[30:33]
	v_mfma_f32_16x16x32_bf16 v[42:45], v[146:149], v[166:169], v[42:45]
	v_mfma_f32_16x16x32_bf16 v[46:49], v[154:157], v[166:169], v[46:49]
	v_mfma_f32_16x16x32_bf16 v[50:53], v[146:149], v[178:181], v[50:53]
	v_mfma_f32_16x16x32_bf16 v[54:57], v[154:157], v[178:181], v[54:57]
	v_mfma_f32_16x16x32_bf16 v[58:61], v[146:149], v[182:185], v[58:61]
	v_mfma_f32_16x16x32_bf16 v[62:65], v[154:157], v[182:185], v[62:65]
	v_mfma_f32_16x16x32_bf16 v[34:37], v[150:153], v[170:173], v[34:37]
	v_mfma_f32_16x16x32_bf16 v[30:33], v[158:161], v[170:173], v[30:33]
	v_mfma_f32_16x16x32_bf16 v[42:45], v[150:153], v[174:177], v[42:45]
	v_mfma_f32_16x16x32_bf16 v[46:49], v[158:161], v[174:177], v[46:49]
	v_mfma_f32_16x16x32_bf16 v[50:53], v[150:153], v[186:189], v[50:53]
	v_mfma_f32_16x16x32_bf16 v[54:57], v[158:161], v[186:189], v[54:57]
	v_mfma_f32_16x16x32_bf16 v[58:61], v[150:153], v[190:193], v[58:61]
	v_mfma_f32_16x16x32_bf16 v[62:65], v[158:161], v[190:193], v[62:65]
	s_setprio 0
	s_barrier
	ds_read_b128 v[130:133], v194
	ds_read_b128 v[134:137], v195
	ds_read_b128 v[138:141], v196
	ds_read_b128 v[142:145], v197
	ds_read_b128 v[146:149], v198
	ds_read_b128 v[150:153], v199
	ds_read_b128 v[154:157], v200
	ds_read_b128 v[158:161], v201
	s_add_i32 s33, s33, 0x100000
	s_mov_b32 m0, s49
	ds_read_b128 v[162:165], v247 offset:32768
	ds_read_b128 v[166:169], v247 offset:34816
	ds_read_b128 v[170:173], v248 offset:32768
	ds_read_b128 v[174:177], v248 offset:34816
	ds_read_b128 v[178:181], v247 offset:36864
	ds_read_b128 v[182:185], v247 offset:38912
	ds_read_b128 v[186:189], v248 offset:36864
	ds_read_b128 v[190:193], v248 offset:38912
	buffer_load_dwordx4 v230, s[8:11], s33 offen lds
	s_mov_b32 m0, s50
	s_nop 0
	buffer_load_dwordx4 v233, s[8:11], s33 offen lds
	s_waitcnt vmcnt(8)
	s_waitcnt lgkmcnt(0)
	s_barrier
	s_setprio 1
	s_waitcnt lgkmcnt(7)
	v_mfma_f32_16x16x32_bf16 v[74:77], v[130:133], v[162:165], v[74:77]
	v_mfma_f32_16x16x32_bf16 v[70:73], v[138:141], v[162:165], v[70:73]
	s_waitcnt lgkmcnt(6)
	v_mfma_f32_16x16x32_bf16 v[66:69], v[130:133], v[166:169], v[66:69]
	v_mfma_f32_16x16x32_bf16 v[82:85], v[138:141], v[166:169], v[82:85]
	s_waitcnt lgkmcnt(3)
	v_mfma_f32_16x16x32_bf16 v[78:81], v[130:133], v[178:181], v[78:81]
	v_mfma_f32_16x16x32_bf16 v[90:93], v[138:141], v[178:181], v[90:93]
	s_waitcnt lgkmcnt(2)
	v_mfma_f32_16x16x32_bf16 v[86:89], v[130:133], v[182:185], v[86:89]
	v_mfma_f32_16x16x32_bf16 v[102:105], v[138:141], v[182:185], v[102:105]
	v_mfma_f32_16x16x32_bf16 v[74:77], v[134:137], v[170:173], v[74:77]
	v_mfma_f32_16x16x32_bf16 v[70:73], v[142:145], v[170:173], v[70:73]
	v_mfma_f32_16x16x32_bf16 v[66:69], v[134:137], v[174:177], v[66:69]
	v_mfma_f32_16x16x32_bf16 v[82:85], v[142:145], v[174:177], v[82:85]
	s_waitcnt lgkmcnt(1)
	v_mfma_f32_16x16x32_bf16 v[78:81], v[134:137], v[186:189], v[78:81]
	v_mfma_f32_16x16x32_bf16 v[90:93], v[142:145], v[186:189], v[90:93]
	s_waitcnt lgkmcnt(0)
	v_mfma_f32_16x16x32_bf16 v[86:89], v[134:137], v[190:193], v[86:89]
	v_mfma_f32_16x16x32_bf16 v[102:105], v[142:145], v[190:193], v[102:105]
	s_setprio 0
	s_setprio 1
	v_mfma_f32_16x16x32_bf16 v[98:101], v[146:149], v[162:165], v[98:101]
	v_mfma_f32_16x16x32_bf16 v[94:97], v[154:157], v[162:165], v[94:97]
	v_mfma_f32_16x16x32_bf16 v[106:109], v[146:149], v[166:169], v[106:109]
	v_mfma_f32_16x16x32_bf16 v[110:113], v[154:157], v[166:169], v[110:113]
	v_mfma_f32_16x16x32_bf16 v[114:117], v[146:149], v[178:181], v[114:117]
	v_mfma_f32_16x16x32_bf16 v[118:121], v[154:157], v[178:181], v[118:121]
	v_mfma_f32_16x16x32_bf16 v[122:125], v[146:149], v[182:185], v[122:125]
	v_mfma_f32_16x16x32_bf16 v[126:129], v[154:157], v[182:185], v[126:129]
	v_mfma_f32_16x16x32_bf16 v[98:101], v[150:153], v[170:173], v[98:101]
	v_mfma_f32_16x16x32_bf16 v[94:97], v[158:161], v[170:173], v[94:97]
	v_mfma_f32_16x16x32_bf16 v[106:109], v[150:153], v[174:177], v[106:109]
	v_mfma_f32_16x16x32_bf16 v[110:113], v[158:161], v[174:177], v[110:113]
	v_mfma_f32_16x16x32_bf16 v[114:117], v[150:153], v[186:189], v[114:117]
	v_mfma_f32_16x16x32_bf16 v[118:121], v[158:161], v[186:189], v[118:121]
	v_mfma_f32_16x16x32_bf16 v[122:125], v[150:153], v[190:193], v[122:125]
	v_mfma_f32_16x16x32_bf16 v[126:129], v[158:161], v[190:193], v[126:129]
	s_setprio 0
	s_barrier
	s_mov_b32 m0, s53
	s_add_i32 s33, s31, 0x80
	ds_read_b128 v[162:165], v247 offset:49152
	ds_read_b128 v[166:169], v247 offset:51200
	ds_read_b128 v[170:173], v248 offset:49152
	ds_read_b128 v[174:177], v248 offset:51200
	ds_read_b128 v[178:181], v247 offset:53248
	ds_read_b128 v[182:185], v247 offset:55296
	ds_read_b128 v[186:189], v248 offset:53248
	ds_read_b128 v[190:193], v248 offset:55296
	buffer_load_dwordx4 v231, s[8:11], s33 offen lds
	s_mov_b32 m0, s54
	s_add_i32 s31, s31, 0x100080
	buffer_load_dwordx4 v234, s[8:11], s33 offen lds
	s_mov_b32 m0, s57
	s_nop 0
	buffer_load_dwordx4 v231, s[8:11], s31 offen lds
	s_mov_b32 m0, s58
	s_nop 0
	buffer_load_dwordx4 v234, s[8:11], s31 offen lds
	s_waitcnt vmcnt(6)
	s_waitcnt lgkmcnt(0)
	s_barrier
	s_setprio 1
	s_waitcnt lgkmcnt(7)
	v_mfma_f32_16x16x32_bf16 v[10:13], v[130:133], v[162:165], v[10:13]
	v_mfma_f32_16x16x32_bf16 v[4:7], v[138:141], v[162:165], v[6:9]
	s_waitcnt lgkmcnt(6)
	s_mov_b32 m0, s55
	s_nop 0
	buffer_load_dwordx4 v230, s[8:11], s30 offen lds
	v_mfma_f32_16x16x32_bf16 v[0:3], v[130:133], v[166:169], v[0:3]
	v_mfma_f32_16x16x32_bf16 v[18:21], v[138:141], v[166:169], v[18:21]
	s_waitcnt lgkmcnt(3)
	v_mfma_f32_16x16x32_bf16 v[14:17], v[130:133], v[178:181], v[14:17]
	v_mfma_f32_16x16x32_bf16 v[26:29], v[138:141], v[178:181], v[26:29]
	s_waitcnt lgkmcnt(2)
	s_mov_b32 m0, s56
	s_nop 0
	buffer_load_dwordx4 v233, s[8:11], s30 offen lds
	v_mfma_f32_16x16x32_bf16 v[22:25], v[130:133], v[182:185], v[22:25]
	v_mfma_f32_16x16x32_bf16 v[38:41], v[138:141], v[182:185], v[38:41]
	v_mfma_f32_16x16x32_bf16 v[10:13], v[134:137], v[170:173], v[10:13]
	v_mfma_f32_16x16x32_bf16 v[6:9], v[142:145], v[170:173], v[4:7]
	v_mfma_f32_16x16x32_bf16 v[2:5], v[134:137], v[174:177], v[0:3]
	v_mfma_f32_16x16x32_bf16 v[18:21], v[142:145], v[174:177], v[18:21]
	s_waitcnt lgkmcnt(1)
	v_mfma_f32_16x16x32_bf16 v[14:17], v[134:137], v[186:189], v[14:17]
	v_mfma_f32_16x16x32_bf16 v[26:29], v[142:145], v[186:189], v[26:29]
	s_waitcnt lgkmcnt(0)
	v_mfma_f32_16x16x32_bf16 v[22:25], v[134:137], v[190:193], v[22:25]
	v_mfma_f32_16x16x32_bf16 v[38:41], v[142:145], v[190:193], v[38:41]
	s_setprio 0
	s_setprio 1
	v_mfma_f32_16x16x32_bf16 v[34:37], v[146:149], v[162:165], v[34:37]
	v_mfma_f32_16x16x32_bf16 v[30:33], v[154:157], v[162:165], v[30:33]
	v_mfma_f32_16x16x32_bf16 v[42:45], v[146:149], v[166:169], v[42:45]
	v_mfma_f32_16x16x32_bf16 v[46:49], v[154:157], v[166:169], v[46:49]
	v_mfma_f32_16x16x32_bf16 v[50:53], v[146:149], v[178:181], v[50:53]
	v_mfma_f32_16x16x32_bf16 v[54:57], v[154:157], v[178:181], v[54:57]
	v_mfma_f32_16x16x32_bf16 v[58:61], v[146:149], v[182:185], v[58:61]
	v_mfma_f32_16x16x32_bf16 v[62:65], v[154:157], v[182:185], v[62:65]
	v_mfma_f32_16x16x32_bf16 v[34:37], v[150:153], v[170:173], v[34:37]
	v_mfma_f32_16x16x32_bf16 v[30:33], v[158:161], v[170:173], v[30:33]
	v_mfma_f32_16x16x32_bf16 v[42:45], v[150:153], v[174:177], v[42:45]
	v_mfma_f32_16x16x32_bf16 v[46:49], v[158:161], v[174:177], v[46:49]
	v_mfma_f32_16x16x32_bf16 v[50:53], v[150:153], v[186:189], v[50:53]
	v_mfma_f32_16x16x32_bf16 v[54:57], v[158:161], v[186:189], v[54:57]
	v_mfma_f32_16x16x32_bf16 v[58:61], v[150:153], v[190:193], v[58:61]
	v_mfma_f32_16x16x32_bf16 v[62:65], v[158:161], v[190:193], v[62:65]
	s_setprio 0
	s_barrier
	s_add_i32 s4, s4, 2
	s_addk_i32 s5, 0x100
	s_cmp_gt_u32 s4, 61
	s_cbranch_scc0 .LBB0_1251
	s_and_b64 vcc, exec, s[18:19]
	s_cbranch_vccz .LBB0_1254
	s_barrier
